# mixer-A PV2 row-sum chain: five identity (+0.0) adds removed
# speedup vs baseline: 1.0211x; 1.0211x over previous
.Lattn_dma_done_a:
	v_exp_f32_e32 v172, v128
	v_exp_f32_e32 v170, v129
	v_exp_f32_e32 v176, v130
	v_exp_f32_e32 v168, v131
	v_exp_f32_e32 v182, v132
	v_exp_f32_e32 v178, v133
	v_exp_f32_e32 v188, v134
	v_exp_f32_e32 v174, v135
	v_exp_f32_e32 v192, v136
	v_exp_f32_e32 v186, v137
	v_exp_f32_e32 v194, v138
	v_exp_f32_e32 v180, v139
	v_exp_f32_e32 v196, v140
	v_exp_f32_e32 v190, v141
	v_exp_f32_e32 v198, v142
	v_exp_f32_e32 v184, v143
	v_cvt_pk_bf16_f32 v144, v173, v169
	v_cvt_pk_bf16_f32 v145, v177, v171
	v_cvt_pk_bf16_f32 v146, v183, v175
	v_cvt_pk_bf16_f32 v147, v189, v179
	v_cvt_pk_bf16_f32 v148, v193, v181
	v_cvt_pk_bf16_f32 v149, v195, v187
	v_cvt_pk_bf16_f32 v150, v197, v185
	v_cvt_pk_bf16_f32 v151, v199, v191
	v_cvt_pk_bf16_f32 v128, v172, v170
	v_cvt_pk_bf16_f32 v129, v176, v168
	v_cvt_pk_bf16_f32 v130, v182, v178
	v_cvt_pk_bf16_f32 v131, v188, v174
	v_cvt_pk_bf16_f32 v132, v192, v186
	v_cvt_pk_bf16_f32 v133, v194, v180
	v_cvt_pk_bf16_f32 v134, v196, v190
	v_cvt_pk_bf16_f32 v135, v198, v184
	v_add3_u32 v160, s7, v162, v160
	v_xad_u32 v252, v163, 64, s7
	v_add_u32_e32 v203, s7, v203
	v_add_u32_e32 v205, s7, v206
	ds_read_b64_tr_b16 v[136:137], v160 offset:32768
	ds_read_b64_tr_b16 v[138:139], v160 offset:34816
	ds_read_b64_tr_b16 v[140:141], v160 offset:36864
	ds_read_b64_tr_b16 v[142:143], v160 offset:38912
	ds_read_b64_tr_b16 v[152:153], v252 offset:32768
	ds_read_b64_tr_b16 v[154:155], v252 offset:34816
	ds_read_b64_tr_b16 v[156:157], v252 offset:36864
	ds_read_b64_tr_b16 v[158:159], v252 offset:38912
	ds_read_b64_tr_b16 v[208:209], v203 offset:32768
	ds_read_b64_tr_b16 v[210:211], v203 offset:34816
	ds_read_b64_tr_b16 v[212:213], v203 offset:36864
	ds_read_b64_tr_b16 v[214:215], v203 offset:38912
	ds_read_b64_tr_b16 v[216:217], v205 offset:32768
	ds_read_b64_tr_b16 v[218:219], v205 offset:34816
	ds_read_b64_tr_b16 v[220:221], v205 offset:36864
	ds_read_b64_tr_b16 v[222:223], v205 offset:38912
	s_waitcnt lgkmcnt(14)
	v_mfma_f32_32x32x16_bf16 v[64:79], v[144:147], v[136:139], v[64:79]
	v_mfma_f32_32x32x16_bf16 v[0:15], v[128:131], v[136:139], v[0:15]
	s_waitcnt lgkmcnt(10)
	v_mfma_f32_32x32x16_bf16 v[80:95], v[144:147], v[152:155], v[80:95]
	v_mfma_f32_32x32x16_bf16 v[16:31], v[128:131], v[152:155], v[16:31]
	s_waitcnt lgkmcnt(6)
	v_mfma_f32_32x32x16_bf16 v[96:111], v[144:147], v[208:211], v[96:111]
	v_mfma_f32_32x32x16_bf16 v[32:47], v[128:131], v[208:211], v[32:47]
	s_waitcnt lgkmcnt(2)
	v_mfma_f32_32x32x16_bf16 v[112:127], v[144:147], v[216:219], v[112:127]
	v_mfma_f32_32x32x16_bf16 v[48:63], v[128:131], v[216:219], v[48:63]
	v_mfma_f32_32x32x16_bf16 v[64:79], v[148:151], v[140:143], v[64:79]
	v_mfma_f32_32x32x16_bf16 v[0:15], v[132:135], v[140:143], v[0:15]
	v_mfma_f32_32x32x16_bf16 v[80:95], v[148:151], v[156:159], v[80:95]
	v_mfma_f32_32x32x16_bf16 v[16:31], v[132:135], v[156:159], v[16:31]
	v_mfma_f32_32x32x16_bf16 v[96:111], v[148:151], v[212:215], v[96:111]
	v_mfma_f32_32x32x16_bf16 v[32:47], v[132:135], v[212:215], v[32:47]
	s_waitcnt lgkmcnt(0)
	v_mfma_f32_32x32x16_bf16 v[112:127], v[148:151], v[220:223], v[112:127]
	v_mfma_f32_32x32x16_bf16 v[48:63], v[132:135], v[220:223], v[48:63]
	ds_read_b128 v[128:131], v207 offset:4096
	ds_read_b128 v[132:135], v224
	ds_read_b128 v[136:139], v225 offset:4096
	ds_read_b128 v[140:143], v226
	s_waitcnt lgkmcnt(2)
	v_mfma_f32_32x32x16_bf16 v[144:159], v[128:131], v[132:135], 0
	ds_read_b128 v[128:131], v227 offset:4096
	ds_read_b128 v[132:135], v228
	s_waitcnt lgkmcnt(2)
	v_mfma_f32_32x32x16_bf16 v[144:159], v[136:139], v[140:143], v[144:159]
	ds_read_b128 v[136:139], v230 offset:4096
	ds_read_b128 v[140:143], v232
	s_waitcnt lgkmcnt(2)
	v_mfma_f32_32x32x16_bf16 v[144:159], v[128:131], v[132:135], v[144:159]
	ds_read_b128 v[128:131], v207 offset:12288
	ds_read_b128 v[132:135], v224 offset:4096
	s_waitcnt lgkmcnt(2)
	v_mfma_f32_32x32x16_bf16 v[144:159], v[136:139], v[140:143], v[144:159]
	ds_read_b128 v[208:211], v225 offset:12288
	ds_read_b128 v[212:215], v226 offset:4096
	s_waitcnt lgkmcnt(2)
	v_mfma_f32_32x32x16_bf16 v[128:143], v[128:131], v[132:135], 0
	s_nop 7
	v_exp_f32_e32 v229, v144
	v_exp_f32_e32 v145, v145
	v_exp_f32_e32 v231, v146
	v_exp_f32_e32 v147, v147
	ds_read_b128 v[216:219], v227 offset:12288
	ds_read_b128 v[220:223], v228 offset:4096
	s_waitcnt lgkmcnt(2)
	v_mfma_f32_32x32x16_bf16 v[128:143], v[208:211], v[212:215], v[128:143]
	v_exp_f32_e32 v233, v148
	v_exp_f32_e32 v235, v149
	v_exp_f32_e32 v237, v150
	v_exp_f32_e32 v239, v151
	ds_read_b128 v[148:151], v230 offset:12288
	ds_read_b128 v[208:211], v232 offset:4096
	s_waitcnt lgkmcnt(2)
	v_mfma_f32_32x32x16_bf16 v[128:143], v[216:219], v[220:223], v[128:143]
	v_exp_f32_e32 v241, v152
	v_exp_f32_e32 v243, v153
	v_exp_f32_e32 v245, v154
	v_exp_f32_e32 v247, v155
	s_waitcnt lgkmcnt(0)
	v_mfma_f32_32x32x16_bf16 v[128:143], v[148:151], v[208:211], v[128:143]
	v_exp_f32_e32 v249, v156
	v_exp_f32_e32 v251, v157
	v_exp_f32_e32 v207, v158
	v_exp_f32_e32 v163, v159
	s_nop 7
	v_exp_f32_e32 v228, v128
	v_exp_f32_e32 v146, v129
	v_exp_f32_e32 v230, v130
	v_exp_f32_e32 v144, v131
	v_exp_f32_e32 v232, v132
	v_exp_f32_e32 v238, v133
	v_exp_f32_e32 v236, v134
	v_exp_f32_e32 v234, v135
	v_exp_f32_e32 v240, v136
	v_exp_f32_e32 v246, v137
	v_exp_f32_e32 v244, v138
	v_exp_f32_e32 v242, v139
	v_exp_f32_e32 v248, v140
	v_exp_f32_e32 v162, v141
	v_exp_f32_e32 v206, v142
	v_exp_f32_e32 v250, v143
	v_cvt_pk_bf16_f32 v148, v229, v145
	v_cvt_pk_bf16_f32 v149, v231, v147
	v_cvt_pk_bf16_f32 v150, v233, v235
	v_cvt_pk_bf16_f32 v151, v237, v239
	v_cvt_pk_bf16_f32 v152, v241, v243
	v_cvt_pk_bf16_f32 v153, v245, v247
	v_cvt_pk_bf16_f32 v154, v249, v251
	v_cvt_pk_bf16_f32 v155, v207, v163
	v_cvt_pk_bf16_f32 v128, v228, v146
	v_cvt_pk_bf16_f32 v129, v230, v144
	v_cvt_pk_bf16_f32 v130, v232, v238
	v_cvt_pk_bf16_f32 v131, v236, v234
	v_cvt_pk_bf16_f32 v132, v240, v246
	v_cvt_pk_bf16_f32 v133, v244, v242
	v_cvt_pk_bf16_f32 v134, v248, v162
	v_cvt_pk_bf16_f32 v135, v206, v250
	s_addk_i32 s5, 0x4000
	s_add_i32 s4, s4, 0x10000
	s_and_b32 s7, s5, 0x4000
	ds_read_b64_tr_b16 v[136:137], v160 offset:40960
	ds_read_b64_tr_b16 v[138:139], v160 offset:43008
	ds_read_b64_tr_b16 v[140:141], v160 offset:45056
	ds_read_b64_tr_b16 v[142:143], v160 offset:47104
	ds_read_b64_tr_b16 v[156:157], v252 offset:40960
	ds_read_b64_tr_b16 v[158:159], v252 offset:43008
	ds_read_b64_tr_b16 v[208:209], v252 offset:45056
	ds_read_b64_tr_b16 v[210:211], v252 offset:47104
	ds_read_b64_tr_b16 v[212:213], v203 offset:40960
	ds_read_b64_tr_b16 v[214:215], v203 offset:43008
	ds_read_b64_tr_b16 v[216:217], v203 offset:45056
	ds_read_b64_tr_b16 v[218:219], v203 offset:47104
	ds_read_b64_tr_b16 v[220:221], v205 offset:40960
	ds_read_b64_tr_b16 v[222:223], v205 offset:43008
	ds_read_b64_tr_b16 v[224:225], v205 offset:45056
	ds_read_b64_tr_b16 v[226:227], v205 offset:47104
	s_waitcnt lgkmcnt(14)
	v_mfma_f32_32x32x16_bf16 v[64:79], v[148:151], v[136:139], v[64:79]
	v_mfma_f32_32x32x16_bf16 v[0:15], v[128:131], v[136:139], v[0:15]
	s_waitcnt lgkmcnt(10)
	v_mfma_f32_32x32x16_bf16 v[80:95], v[148:151], v[156:159], v[80:95]
	v_mfma_f32_32x32x16_bf16 v[16:31], v[128:131], v[156:159], v[16:31]
	s_waitcnt lgkmcnt(6)
	v_mfma_f32_32x32x16_bf16 v[96:111], v[148:151], v[212:215], v[96:111]
	v_mfma_f32_32x32x16_bf16 v[32:47], v[128:131], v[212:215], v[32:47]
	s_waitcnt lgkmcnt(2)
	v_mfma_f32_32x32x16_bf16 v[112:127], v[148:151], v[220:223], v[112:127]
	v_mfma_f32_32x32x16_bf16 v[48:63], v[128:131], v[220:223], v[48:63]
	v_add_f32_e64 v128, v172, v176
	v_add_f32_e64 v129, v173, v177
	v_add_f32_e64 v130, v168, v170
	v_add_f32_e64 v131, v169, v171
	v_pk_add_f32 v[136:137], v[182:183], v[188:189]
	v_pk_add_f32 v[128:129], v[136:137], v[128:129]
	v_pk_add_f32 v[136:137], v[174:175], v[178:179]
	v_pk_add_f32 v[138:139], v[232:233], v[236:237]
	v_pk_add_f32 v[130:131], v[136:137], v[130:131]
	v_pk_add_f32 v[136:137], v[192:193], v[194:195]
	v_mfma_f32_32x32x16_bf16 v[64:79], v[152:155], v[140:143], v[64:79]
	v_add_f32_e64 v128, v136, v128
	v_add_f32_e64 v129, v137, v129
	v_add_f32_e64 v136, v180, v186
	v_add_f32_e64 v137, v181, v187
	v_add_f32_e64 v130, v136, v130
	v_add_f32_e64 v131, v137, v131
	v_pk_add_f32 v[136:137], v[196:197], v[198:199]
	s_nop 0
	v_pk_add_f32 v[128:129], v[136:137], v[128:129]
	v_pk_add_f32 v[136:137], v[184:185], v[190:191]
	v_mfma_f32_32x32x16_bf16 v[0:15], v[132:135], v[140:143], v[0:15]
	v_add_f32_e64 v130, v136, v130
	v_add_f32_e64 v131, v137, v131
	v_add_f32_e64 v136, v144, v146
	v_add_f32_e64 v137, v145, v147
	v_add_f32_e64 v128, v128, v130
	v_add_f32_e64 v129, v129, v131
	v_pk_add_f32 v[130:131], v[228:229], v[230:231]
	v_pk_add_f32 v[128:129], v[166:167], v[128:129]
	v_mfma_f32_32x32x16_bf16 v[80:95], v[152:155], v[208:211], v[80:95]
	v_add_f32_e64 v130, v138, v130
	v_add_f32_e64 v131, v139, v131
	v_add_f32_e64 v138, v234, v238
	v_add_f32_e64 v139, v235, v239
	v_add_f32_e64 v136, v138, v136
	v_add_f32_e64 v137, v139, v137
	v_pk_add_f32 v[138:139], v[240:241], v[244:245]
	s_nop 0
	v_pk_add_f32 v[130:131], v[138:139], v[130:131]
	v_mfma_f32_32x32x16_bf16 v[16:31], v[132:135], v[208:211], v[16:31]
	v_add_f32_e64 v138, v242, v246
	v_add_f32_e64 v139, v243, v247
	v_add_f32_e64 v136, v138, v136
	v_add_f32_e64 v137, v139, v137
	v_add_f32_e64 v138, v248, v206
	v_add_f32_e64 v139, v249, v207
	v_pk_add_f32 v[130:131], v[138:139], v[130:131]
	v_pk_add_f32 v[138:139], v[250:251], v[162:163]
	v_mfma_f32_32x32x16_bf16 v[96:111], v[152:155], v[216:219], v[96:111]
	v_add_f32_e64 v136, v138, v136
	v_add_f32_e64 v137, v139, v137
	v_add_f32_e64 v130, v130, v136
	v_add_f32_e64 v131, v131, v137
	v_add_f32_e64 v166, v128, v130
	v_add_f32_e64 v167, v129, v131
	v_mfma_f32_32x32x16_bf16 v[32:47], v[132:135], v[216:219], v[32:47]
	s_waitcnt lgkmcnt(0)
	v_mfma_f32_32x32x16_bf16 v[112:127], v[152:155], v[224:227], v[112:127]
	v_mfma_f32_32x32x16_bf16 v[48:63], v[132:135], v[224:227], v[48:63]
	s_waitcnt vmcnt(0)
	s_cmp_eq_u32 s4, 0x400000
	s_cbranch_scc0 .Lattn_head_a
	s_barrier
